# QKV epilogue sum-of-squares pass: 8 per-row rs loads hoisted to pass start with counted waits, on top of v15
# speedup vs baseline: 1.0015x; 1.0015x over previous
;     __device__ __forceinline__ void operator()(const f32x4 (&acc)[2][2][4][2], const pg8::Unit& u, int wr, int wc, int fr, int fq) const {
;     ...
;             for (int m = 0; m < 4; ++m) { const float sc = rs[row0 + ai * 128 + m * 16];
; #pragma unroll
;                 for (int bj = 0; bj < 2; ++bj) { const f32x4 v0 = acc[ai][bj][m][0] * sc, v1 = acc[ai][bj][m][1] * sc;
;                     float s = (v0[0] * v0[0] + v0[1] * v0[1]) + (v0[2] * v0[2] + v0[3] * v0[3]) + (v1[0] * v1[0] + v1[1] * v1[1]) + (v1[2] * v1[2] + v1[3] * v1[3]);
;                     s += __shfl_xor(s, 16); s += __shfl_xor(s, 32);
;                     if (fq == 0) ss[(bj * 4 + wc) * 256 + ai * 128 + wr * 64 + m * 16 + fr] = s; } }
.LBB0_175:
	v_lshl_add_u64 v[152:153], v[148:149], 2, s[22:23]
	global_load_dword v130, v[152:153], off
	global_load_dword v174, v[152:153], off offset:64
	global_load_dword v175, v[152:153], off offset:128
	global_load_dword v176, v[152:153], off offset:192
	global_load_dword v177, v[152:153], off offset:512
	global_load_dword v178, v[152:153], off offset:576
	global_load_dword v179, v[152:153], off offset:640
	global_load_dword v180, v[152:153], off offset:704
	v_and_b32_e32 v131, 64, v235
	v_add_u32_e32 v131, 64, v131
	v_xor_b32_e32 v128, 16, v235
	v_cmp_lt_i32_e32 vcc, v128, v131
	s_waitcnt vmcnt(7)
	v_pk_mul_f32 v[132:133], v[126:127], v[130:131] op_sel_hi:[1,0]
	v_pk_mul_f32 v[134:135], v[124:125], v[130:131] op_sel_hi:[1,0]
	v_pk_mul_f32 v[138:139], v[120:121], v[130:131] op_sel_hi:[1,0]
	v_mul_f32_e32 v135, v135, v135
	v_mul_f32_e32 v133, v133, v133
	v_pk_mul_f32 v[136:137], v[122:123], v[130:131] op_sel_hi:[1,0]
	v_mul_f32_e32 v139, v139, v139
	v_fmac_f32_e32 v135, v134, v134
	v_fmac_f32_e32 v133, v132, v132
	v_mul_f32_e32 v137, v137, v137
	v_fmac_f32_e32 v139, v138, v138
	v_add_f32_e32 v132, v135, v133
	v_cndmask_b32_e32 v128, v235, v128, vcc
	v_add_f32_e32 v132, v139, v132
	v_fmac_f32_e32 v137, v136, v136
	v_lshlrev_b32_e32 v128, 2, v128
	v_add_f32_e32 v133, v137, v132
	ds_bpermute_b32 v134, v128, v133
	v_xor_b32_e32 v132, 32, v235
	v_cmp_lt_i32_e32 vcc, v132, v131
	s_nop 1
	v_cndmask_b32_e32 v131, v235, v132, vcc
	v_lshlrev_b32_e32 v132, 2, v131
	s_waitcnt lgkmcnt(0)
	v_add_f32_e32 v131, v133, v134
	ds_bpermute_b32 v133, v132, v131
	s_and_saveexec_b64 s[28:29], s[36:37]
	s_cbranch_execz .LBB0_177
	s_waitcnt lgkmcnt(0)
	v_add_f32_e32 v131, v131, v133
	ds_write_b32 v229, v131

;     __device__ __forceinline__ void operator()(const f32x4 (&acc)[2][2][4][2], const pg8::Unit& u, int wr, int wc, int fr, int fq) const {
;     ...
;             for (int m = 0; m < 4; ++m) { const float sc = rs[row0 + ai * 128 + m * 16];
; #pragma unroll
;                 for (int bj = 0; bj < 2; ++bj) { const f32x4 v0 = acc[ai][bj][m][0] * sc, v1 = acc[ai][bj][m][1] * sc;
;                     float s = (v0[0] * v0[0] + v0[1] * v0[1]) + (v0[2] * v0[2] + v0[3] * v0[3]) + (v1[0] * v1[0] + v1[1] * v1[1]) + (v1[2] * v1[2] + v1[3] * v1[3]);
;                     s += __shfl_xor(s, 16); s += __shfl_xor(s, 32);
;                     if (fq == 0) ss[(bj * 4 + wc) * 256 + ai * 128 + wr * 64 + m * 16 + fr] = s; } }
.LBB0_179:
	s_or_b64 exec, exec, s[28:29]
	s_waitcnt vmcnt(6) lgkmcnt(0)
	v_mov_b32_e32 v130, v174
	v_pk_mul_f32 v[134:135], v[110:111], v[130:131] op_sel_hi:[1,0]
	v_pk_mul_f32 v[136:137], v[108:109], v[130:131] op_sel_hi:[1,0]
	v_pk_mul_f32 v[138:139], v[106:107], v[130:131] op_sel_hi:[1,0]
	v_pk_mul_f32 v[140:141], v[104:105], v[130:131] op_sel_hi:[1,0]
	v_mul_f32_e32 v131, v137, v137
	v_mul_f32_e32 v133, v135, v135
	v_mul_f32_e32 v135, v141, v141
	v_fmac_f32_e32 v131, v136, v136
	v_fmac_f32_e32 v133, v134, v134
	v_mul_f32_e32 v137, v139, v139
	v_fmac_f32_e32 v135, v140, v140
	v_add_f32_e32 v131, v131, v133
	v_add_f32_e32 v131, v135, v131
	v_fmac_f32_e32 v137, v138, v138
	v_add_f32_e32 v131, v137, v131
	ds_bpermute_b32 v133, v128, v131
	s_waitcnt lgkmcnt(0)
	v_add_f32_e32 v131, v131, v133
	ds_bpermute_b32 v133, v132, v131
	s_and_saveexec_b64 s[28:29], s[36:37]
	s_cbranch_execz .LBB0_181
	s_waitcnt lgkmcnt(0)
	v_add_f32_e32 v131, v131, v133
	ds_write_b32 v229, v131 offset:64

;     __device__ __forceinline__ void operator()(const f32x4 (&acc)[2][2][4][2], const pg8::Unit& u, int wr, int wc, int fr, int fq) const {
;     ...
;             for (int m = 0; m < 4; ++m) { const float sc = rs[row0 + ai * 128 + m * 16];
; #pragma unroll
;                 for (int bj = 0; bj < 2; ++bj) { const f32x4 v0 = acc[ai][bj][m][0] * sc, v1 = acc[ai][bj][m][1] * sc;
;                     float s = (v0[0] * v0[0] + v0[1] * v0[1]) + (v0[2] * v0[2] + v0[3] * v0[3]) + (v1[0] * v1[0] + v1[1] * v1[1]) + (v1[2] * v1[2] + v1[3] * v1[3]);
;                     s += __shfl_xor(s, 16); s += __shfl_xor(s, 32);
;                     if (fq == 0) ss[(bj * 4 + wc) * 256 + ai * 128 + wr * 64 + m * 16 + fr] = s; } }
.LBB0_183:
	s_or_b64 exec, exec, s[28:29]
	s_waitcnt vmcnt(5) lgkmcnt(0)
	v_mov_b32_e32 v130, v175
	v_pk_mul_f32 v[134:135], v[94:95], v[130:131] op_sel_hi:[1,0]
	v_pk_mul_f32 v[136:137], v[92:93], v[130:131] op_sel_hi:[1,0]
	v_pk_mul_f32 v[138:139], v[90:91], v[130:131] op_sel_hi:[1,0]
	v_pk_mul_f32 v[140:141], v[88:89], v[130:131] op_sel_hi:[1,0]
	v_mul_f32_e32 v131, v137, v137
	v_mul_f32_e32 v133, v135, v135
	v_mul_f32_e32 v135, v141, v141
	v_fmac_f32_e32 v131, v136, v136
	v_fmac_f32_e32 v133, v134, v134
	v_mul_f32_e32 v137, v139, v139
	v_fmac_f32_e32 v135, v140, v140
	v_add_f32_e32 v131, v131, v133
	v_add_f32_e32 v131, v135, v131
	v_fmac_f32_e32 v137, v138, v138
	v_add_f32_e32 v131, v137, v131
	ds_bpermute_b32 v133, v128, v131
	s_waitcnt lgkmcnt(0)
	v_add_f32_e32 v131, v131, v133
	ds_bpermute_b32 v133, v132, v131
	s_and_saveexec_b64 s[28:29], s[36:37]
	s_cbranch_execz .LBB0_185
	s_waitcnt lgkmcnt(0)
	v_add_f32_e32 v131, v131, v133
	ds_write_b32 v229, v131 offset:128

;     __device__ __forceinline__ void operator()(const f32x4 (&acc)[2][2][4][2], const pg8::Unit& u, int wr, int wc, int fr, int fq) const {
;     ...
;             for (int m = 0; m < 4; ++m) { const float sc = rs[row0 + ai * 128 + m * 16];
; #pragma unroll
;                 for (int bj = 0; bj < 2; ++bj) { const f32x4 v0 = acc[ai][bj][m][0] * sc, v1 = acc[ai][bj][m][1] * sc;
;                     float s = (v0[0] * v0[0] + v0[1] * v0[1]) + (v0[2] * v0[2] + v0[3] * v0[3]) + (v1[0] * v1[0] + v1[1] * v1[1]) + (v1[2] * v1[2] + v1[3] * v1[3]);
;                     s += __shfl_xor(s, 16); s += __shfl_xor(s, 32);
;                     if (fq == 0) ss[(bj * 4 + wc) * 256 + ai * 128 + wr * 64 + m * 16 + fr] = s; } }
.LBB0_187:
	s_or_b64 exec, exec, s[28:29]
	s_waitcnt vmcnt(4) lgkmcnt(0)
	v_mov_b32_e32 v130, v176
	v_pk_mul_f32 v[134:135], v[78:79], v[130:131] op_sel_hi:[1,0]
	v_pk_mul_f32 v[136:137], v[76:77], v[130:131] op_sel_hi:[1,0]
	v_pk_mul_f32 v[138:139], v[74:75], v[130:131] op_sel_hi:[1,0]
	v_pk_mul_f32 v[140:141], v[72:73], v[130:131] op_sel_hi:[1,0]
	v_mul_f32_e32 v131, v137, v137
	v_mul_f32_e32 v133, v135, v135
	v_mul_f32_e32 v135, v141, v141
	v_fmac_f32_e32 v131, v136, v136
	v_fmac_f32_e32 v133, v134, v134
	v_mul_f32_e32 v137, v139, v139
	v_fmac_f32_e32 v135, v140, v140
	v_add_f32_e32 v131, v131, v133
	v_add_f32_e32 v131, v135, v131
	v_fmac_f32_e32 v137, v138, v138
	v_add_f32_e32 v131, v137, v131
	ds_bpermute_b32 v133, v128, v131
	s_waitcnt lgkmcnt(0)
	v_add_f32_e32 v131, v131, v133
	ds_bpermute_b32 v133, v132, v131
	s_and_saveexec_b64 s[28:29], s[36:37]
	s_cbranch_execz .LBB0_189
	s_waitcnt lgkmcnt(0)
	v_add_f32_e32 v131, v131, v133
	ds_write_b32 v229, v131 offset:192

;     __device__ __forceinline__ void operator()(const f32x4 (&acc)[2][2][4][2], const pg8::Unit& u, int wr, int wc, int fr, int fq) const {
;     ...
;         for (int ai = 0; ai < 2; ++ai)
; #pragma unroll
;             for (int m = 0; m < 4; ++m) { const float sc = rs[row0 + ai * 128 + m * 16];
; #pragma unroll
;                 for (int bj = 0; bj < 2; ++bj) { const f32x4 v0 = acc[ai][bj][m][0] * sc, v1 = acc[ai][bj][m][1] * sc;
;                     float s = (v0[0] * v0[0] + v0[1] * v0[1]) + (v0[2] * v0[2] + v0[3] * v0[3]) + (v1[0] * v1[0] + v1[1] * v1[1]) + (v1[2] * v1[2] + v1[3] * v1[3]);
;                     s += __shfl_xor(s, 16); s += __shfl_xor(s, 32);
;                     if (fq == 0) ss[(bj * 4 + wc) * 256 + ai * 128 + wr * 64 + m * 16 + fr] = s; } }
.LBB0_191:
	s_or_b64 exec, exec, s[28:29]
	s_waitcnt vmcnt(3) lgkmcnt(0)
	v_mov_b32_e32 v130, v177
	v_pk_mul_f32 v[134:135], v[62:63], v[130:131] op_sel_hi:[1,0]
	v_pk_mul_f32 v[136:137], v[60:61], v[130:131] op_sel_hi:[1,0]
	v_pk_mul_f32 v[138:139], v[58:59], v[130:131] op_sel_hi:[1,0]
	v_pk_mul_f32 v[140:141], v[56:57], v[130:131] op_sel_hi:[1,0]
	v_mul_f32_e32 v131, v137, v137
	v_mul_f32_e32 v133, v135, v135
	v_mul_f32_e32 v135, v141, v141
	v_fmac_f32_e32 v131, v136, v136
	v_fmac_f32_e32 v133, v134, v134
	v_mul_f32_e32 v137, v139, v139
	v_fmac_f32_e32 v135, v140, v140
	v_add_f32_e32 v131, v131, v133
	v_add_f32_e32 v131, v135, v131
	v_fmac_f32_e32 v137, v138, v138
	v_add_f32_e32 v131, v137, v131
	ds_bpermute_b32 v133, v128, v131
	s_waitcnt lgkmcnt(0)
	v_add_f32_e32 v131, v131, v133
	ds_bpermute_b32 v133, v132, v131
	s_and_saveexec_b64 s[28:29], s[36:37]
	s_cbranch_execz .LBB0_193
	s_waitcnt lgkmcnt(0)
	v_add_f32_e32 v131, v131, v133
	ds_write_b32 v229, v131 offset:512

;     __device__ __forceinline__ void operator()(const f32x4 (&acc)[2][2][4][2], const pg8::Unit& u, int wr, int wc, int fr, int fq) const {
;     ...
;         for (int ai = 0; ai < 2; ++ai)
; #pragma unroll
;             for (int m = 0; m < 4; ++m) { const float sc = rs[row0 + ai * 128 + m * 16];
; #pragma unroll
;                 for (int bj = 0; bj < 2; ++bj) { const f32x4 v0 = acc[ai][bj][m][0] * sc, v1 = acc[ai][bj][m][1] * sc;
;                     float s = (v0[0] * v0[0] + v0[1] * v0[1]) + (v0[2] * v0[2] + v0[3] * v0[3]) + (v1[0] * v1[0] + v1[1] * v1[1]) + (v1[2] * v1[2] + v1[3] * v1[3]);
;                     s += __shfl_xor(s, 16); s += __shfl_xor(s, 32);
;                     if (fq == 0) ss[(bj * 4 + wc) * 256 + ai * 128 + wr * 64 + m * 16 + fr] = s; } }
.LBB0_195:
	s_or_b64 exec, exec, s[28:29]
	s_waitcnt vmcnt(2) lgkmcnt(0)
	v_mov_b32_e32 v130, v178
	v_pk_mul_f32 v[134:135], v[46:47], v[130:131] op_sel_hi:[1,0]
	v_pk_mul_f32 v[136:137], v[44:45], v[130:131] op_sel_hi:[1,0]
	v_pk_mul_f32 v[138:139], v[42:43], v[130:131] op_sel_hi:[1,0]
	v_pk_mul_f32 v[140:141], v[40:41], v[130:131] op_sel_hi:[1,0]
	v_mul_f32_e32 v131, v137, v137
	v_mul_f32_e32 v133, v135, v135
	v_mul_f32_e32 v135, v141, v141
	v_fmac_f32_e32 v131, v136, v136
	v_fmac_f32_e32 v133, v134, v134
	v_mul_f32_e32 v137, v139, v139
	v_fmac_f32_e32 v135, v140, v140
	v_add_f32_e32 v131, v131, v133
	v_add_f32_e32 v131, v135, v131
	v_fmac_f32_e32 v137, v138, v138
	v_add_f32_e32 v131, v137, v131
	ds_bpermute_b32 v133, v128, v131
	s_waitcnt lgkmcnt(0)
	v_add_f32_e32 v131, v131, v133
	ds_bpermute_b32 v133, v132, v131
	s_and_saveexec_b64 s[28:29], s[36:37]
	s_cbranch_execz .LBB0_197
	s_waitcnt lgkmcnt(0)
	v_add_f32_e32 v131, v131, v133
	ds_write_b32 v229, v131 offset:576

;     __device__ __forceinline__ void operator()(const f32x4 (&acc)[2][2][4][2], const pg8::Unit& u, int wr, int wc, int fr, int fq) const {
;     ...
;         for (int ai = 0; ai < 2; ++ai)
; #pragma unroll
;             for (int m = 0; m < 4; ++m) { const float sc = rs[row0 + ai * 128 + m * 16];
; #pragma unroll
;                 for (int bj = 0; bj < 2; ++bj) { const f32x4 v0 = acc[ai][bj][m][0] * sc, v1 = acc[ai][bj][m][1] * sc;
;                     float s = (v0[0] * v0[0] + v0[1] * v0[1]) + (v0[2] * v0[2] + v0[3] * v0[3]) + (v1[0] * v1[0] + v1[1] * v1[1]) + (v1[2] * v1[2] + v1[3] * v1[3]);
;                     s += __shfl_xor(s, 16); s += __shfl_xor(s, 32);
;                     if (fq == 0) ss[(bj * 4 + wc) * 256 + ai * 128 + wr * 64 + m * 16 + fr] = s; } }
.LBB0_199:
	s_or_b64 exec, exec, s[28:29]
	s_waitcnt vmcnt(1) lgkmcnt(0)
	v_mov_b32_e32 v130, v179
	v_pk_mul_f32 v[134:135], v[30:31], v[130:131] op_sel_hi:[1,0]
	v_pk_mul_f32 v[136:137], v[28:29], v[130:131] op_sel_hi:[1,0]
	v_pk_mul_f32 v[138:139], v[26:27], v[130:131] op_sel_hi:[1,0]
	v_pk_mul_f32 v[140:141], v[24:25], v[130:131] op_sel_hi:[1,0]
	v_mul_f32_e32 v131, v137, v137
	v_mul_f32_e32 v133, v135, v135
	v_mul_f32_e32 v135, v141, v141
	v_fmac_f32_e32 v131, v136, v136
	v_fmac_f32_e32 v133, v134, v134
	v_mul_f32_e32 v137, v139, v139
	v_fmac_f32_e32 v135, v140, v140
	v_add_f32_e32 v131, v131, v133
	v_add_f32_e32 v131, v135, v131
	v_fmac_f32_e32 v137, v138, v138
	v_add_f32_e32 v131, v137, v131
	ds_bpermute_b32 v133, v128, v131
	s_waitcnt lgkmcnt(0)
	v_add_f32_e32 v131, v131, v133
	ds_bpermute_b32 v133, v132, v131
	s_and_saveexec_b64 s[28:29], s[36:37]
	s_cbranch_execz .LBB0_201
	s_waitcnt lgkmcnt(0)
	v_add_f32_e32 v131, v131, v133
	ds_write_b32 v229, v131 offset:640

;     __device__ __forceinline__ void operator()(const f32x4 (&acc)[2][2][4][2], const pg8::Unit& u, int wr, int wc, int fr, int fq) const {
;     ...
;         for (int ai = 0; ai < 2; ++ai)
; #pragma unroll
;             for (int m = 0; m < 4; ++m) { const float sc = rs[row0 + ai * 128 + m * 16];
; #pragma unroll
;                 for (int bj = 0; bj < 2; ++bj) { const f32x4 v0 = acc[ai][bj][m][0] * sc, v1 = acc[ai][bj][m][1] * sc;
;                     float s = (v0[0] * v0[0] + v0[1] * v0[1]) + (v0[2] * v0[2] + v0[3] * v0[3]) + (v1[0] * v1[0] + v1[1] * v1[1]) + (v1[2] * v1[2] + v1[3] * v1[3]);
;                     s += __shfl_xor(s, 16); s += __shfl_xor(s, 32);
;                     if (fq == 0) ss[(bj * 4 + wc) * 256 + ai * 128 + wr * 64 + m * 16 + fr] = s; } }
.LBB0_203:
	s_or_b64 exec, exec, s[28:29]
	s_waitcnt vmcnt(0) lgkmcnt(0)
	v_mov_b32_e32 v130, v180
	v_pk_mul_f32 v[134:135], v[14:15], v[130:131] op_sel_hi:[1,0]
	v_pk_mul_f32 v[136:137], v[12:13], v[130:131] op_sel_hi:[1,0]
	v_pk_mul_f32 v[138:139], v[10:11], v[130:131] op_sel_hi:[1,0]
	v_pk_mul_f32 v[140:141], v[8:9], v[130:131] op_sel_hi:[1,0]
	v_mul_f32_e32 v131, v137, v137
	v_mul_f32_e32 v133, v135, v135
	v_mul_f32_e32 v135, v141, v141
	v_fmac_f32_e32 v131, v136, v136
	v_fmac_f32_e32 v133, v134, v134
	v_mul_f32_e32 v137, v139, v139
	v_fmac_f32_e32 v135, v140, v140
	v_add_f32_e32 v131, v131, v133
	v_add_f32_e32 v131, v135, v131
	v_fmac_f32_e32 v137, v138, v138
	v_add_f32_e32 v131, v137, v131
	ds_bpermute_b32 v133, v128, v131
	s_waitcnt lgkmcnt(0)
	v_add_f32_e32 v131, v131, v133
	ds_bpermute_b32 v133, v132, v131
	s_and_saveexec_b64 s[28:29], s[36:37]
	s_cbranch_execz .LBB0_205
	s_waitcnt lgkmcnt(0)
	v_add_f32_e32 v131, v131, v133
	ds_write_b32 v229, v131 offset:704
